# P7 top-k: the four sequential per-token softmax/top-2 blocks collapsed into one block where lanes 2t,2t+1 compute token t (same per-lane arithmetic; inputs gathered per lane with 4 bpermutes + selects
# speedup vs baseline: 1.0283x; 1.0059x over previous
; DEVI void phase_p7(const int TIDX, const int BIDX, const int GDIM, KAP KA, unsigned char* WSB, float* OUTB, int l, unsigned char* smem) {
;     ...
; #pragma unroll 4
;       for (int c = 0; c < 36; ++c) {
;         float4 wv[4];
; #pragma unroll
;         for (int j = 0; j < 4; ++j) wv[j] = *(const float4*)(WR + c * 1024 + j * 256 + lane * 4);
; #pragma unroll
;         for (int t = 0; t < 4; ++t) {
;           float s = 0.f;
; #pragma unroll
;           for (int j = 0; j < 4; ++j) s += v[t][j].x * wv[j].x + v[t][j].y * wv[j].y + v[t][j].z * wv[j].z + v[t][j].w * wv[j].w;
;           s = wave_sum(s);
;           if (lane == c) mine[t] = s;
;         }
;       }
.LBB0_69:
	v_lshl_add_u64 v[80:81], v[42:43], 0, s[0:1]
	s_mov_b64 s[24:25], 0x2221000
	s_mov_b64 s[26:27], 0x2223000
	v_lshl_add_u64 v[90:91], v[80:81], 0, s[24:25]
	v_lshl_add_u64 v[92:93], v[80:81], 0, s[26:27]
	global_load_dwordx4 v[142:145], v[90:91], off offset:-4096
	global_load_dwordx4 v[146:149], v[90:91], off offset:-3072
	global_load_dwordx4 v[150:153], v[90:91], off offset:-2048
	global_load_dwordx4 v[154:157], v[90:91], off offset:-1024
	global_load_dwordx4 v[162:165], v[90:91], off
	global_load_dwordx4 v[166:169], v[90:91], off offset:1024
	global_load_dwordx4 v[170:173], v[90:91], off offset:2048
	global_load_dwordx4 v[174:177], v[90:91], off offset:3072
	global_load_dwordx4 v[178:181], v[92:93], off offset:-4096
	global_load_dwordx4 v[182:185], v[92:93], off offset:-3072
	global_load_dwordx4 v[186:189], v[92:93], off offset:-2048
	global_load_dwordx4 v[190:193], v[92:93], off offset:-1024
	global_load_dwordx4 v[196:199], v[92:93], off
	global_load_dwordx4 v[200:203], v[92:93], off offset:1024
	global_load_dwordx4 v[236:239], v[92:93], off offset:2048
	global_load_dwordx4 v[240:243], v[92:93], off offset:3072
	s_waitcnt vmcnt(14)
	v_mov_b32_e32 v252, v142
	v_mov_b32_e32 v253, v146
	v_mov_b32_e32 v146, v143
	v_mov_b32_e32 v158, v144
	v_mov_b32_e32 v159, v148
	v_mov_b32_e32 v148, v145
	v_pk_mul_f32 v[244:245], v[26:27], v[146:147]
	v_pk_mul_f32 v[246:247], v[56:57], v[146:147]
	v_pk_mul_f32 v[248:249], v[4:5], v[146:147]
	v_pk_mul_f32 v[250:251], v[20:21], v[146:147]
	v_pk_fma_f32 v[244:245], v[24:25], v[252:253], v[244:245]
	v_pk_fma_f32 v[246:247], v[54:55], v[252:253], v[246:247]
	v_pk_fma_f32 v[248:249], v[16:17], v[252:253], v[248:249]
	v_pk_fma_f32 v[250:251], v[14:15], v[252:253], v[250:251]
	v_pk_fma_f32 v[244:245], v[28:29], v[158:159], v[244:245]
	v_pk_fma_f32 v[246:247], v[58:59], v[158:159], v[246:247]
	v_pk_fma_f32 v[248:249], v[18:19], v[158:159], v[248:249]
	v_pk_fma_f32 v[250:251], v[22:23], v[158:159], v[250:251]
	v_pk_fma_f32 v[244:245], v[30:31], v[148:149], v[244:245]
	v_pk_fma_f32 v[246:247], v[60:61], v[148:149], v[246:247]
	v_pk_fma_f32 v[248:249], v[2:3], v[148:149], v[248:249]
	v_pk_fma_f32 v[250:251], v[70:71], v[148:149], v[250:251]
	v_add_f32_e32 v160, 0, v244
	v_add_f32_e32 v194, 0, v246
	v_add_f32_e32 v231, 0, v248
	v_add_f32_e32 v232, 0, v250
	v_add_f32_e32 v160, v160, v245
	v_add_f32_e32 v194, v194, v247
	v_add_f32_e32 v231, v231, v249
	v_add_f32_e32 v232, v232, v251
	s_waitcnt vmcnt(12)
	v_mov_b32_e32 v252, v150
	v_mov_b32_e32 v253, v154
	v_mov_b32_e32 v154, v151
	v_mov_b32_e32 v158, v152
	v_mov_b32_e32 v159, v156
	v_mov_b32_e32 v156, v153
	v_pk_mul_f32 v[244:245], v[48:49], v[154:155]
	v_pk_mul_f32 v[246:247], v[64:65], v[154:155]
	v_pk_mul_f32 v[248:249], v[8:9], v[154:155]
	v_pk_mul_f32 v[250:251], v[74:75], v[154:155]
	v_pk_fma_f32 v[244:245], v[46:47], v[252:253], v[244:245]
	v_pk_fma_f32 v[246:247], v[62:63], v[252:253], v[246:247]
	v_pk_fma_f32 v[248:249], v[6:7], v[252:253], v[248:249]
	v_pk_fma_f32 v[250:251], v[72:73], v[252:253], v[250:251]
	v_pk_fma_f32 v[244:245], v[50:51], v[158:159], v[244:245]
	v_pk_fma_f32 v[246:247], v[66:67], v[158:159], v[246:247]
	v_pk_fma_f32 v[248:249], v[12:13], v[158:159], v[248:249]
	v_pk_fma_f32 v[250:251], v[76:77], v[158:159], v[250:251]
	v_pk_fma_f32 v[244:245], v[52:53], v[156:157], v[244:245]
	v_pk_fma_f32 v[246:247], v[68:69], v[156:157], v[246:247]
	v_pk_fma_f32 v[248:249], v[10:11], v[156:157], v[248:249]
	v_pk_fma_f32 v[250:251], v[78:79], v[156:157], v[250:251]
	v_add_f32_e32 v160, v160, v244
	v_add_f32_e32 v194, v194, v246
	v_add_f32_e32 v231, v231, v248
	v_add_f32_e32 v232, v232, v250
	v_add_f32_e32 v160, v160, v245
	v_add_f32_e32 v194, v194, v247
	v_add_f32_e32 v231, v231, v249
	v_add_f32_e32 v232, v232, v251
	v_cmp_eq_u32_e32 vcc, s0, v44
	v_add_f32_dpp v160, v160, v160 quad_perm:[1,0,3,2] row_mask:0xf bank_mask:0xf bound_ctrl:1
	v_add_f32_dpp v194, v194, v194 quad_perm:[1,0,3,2] row_mask:0xf bank_mask:0xf bound_ctrl:1
	v_add_f32_dpp v231, v231, v231 quad_perm:[1,0,3,2] row_mask:0xf bank_mask:0xf bound_ctrl:1
	v_add_f32_dpp v232, v232, v232 quad_perm:[1,0,3,2] row_mask:0xf bank_mask:0xf bound_ctrl:1
	v_add_f32_dpp v160, v160, v160 quad_perm:[2,3,0,1] row_mask:0xf bank_mask:0xf bound_ctrl:1
	v_add_f32_dpp v194, v194, v194 quad_perm:[2,3,0,1] row_mask:0xf bank_mask:0xf bound_ctrl:1
	v_add_f32_dpp v231, v231, v231 quad_perm:[2,3,0,1] row_mask:0xf bank_mask:0xf bound_ctrl:1
	v_add_f32_dpp v232, v232, v232 quad_perm:[2,3,0,1] row_mask:0xf bank_mask:0xf bound_ctrl:1
	v_add_f32_dpp v160, v160, v160 row_half_mirror row_mask:0xf bank_mask:0xf bound_ctrl:1
	v_add_f32_dpp v194, v194, v194 row_half_mirror row_mask:0xf bank_mask:0xf bound_ctrl:1
	v_add_f32_dpp v231, v231, v231 row_half_mirror row_mask:0xf bank_mask:0xf bound_ctrl:1
	v_add_f32_dpp v232, v232, v232 row_half_mirror row_mask:0xf bank_mask:0xf bound_ctrl:1
	v_add_f32_dpp v160, v160, v160 row_mirror row_mask:0xf bank_mask:0xf bound_ctrl:1
	v_add_f32_dpp v194, v194, v194 row_mirror row_mask:0xf bank_mask:0xf bound_ctrl:1
	v_add_f32_dpp v231, v231, v231 row_mirror row_mask:0xf bank_mask:0xf bound_ctrl:1
	v_add_f32_dpp v232, v232, v232 row_mirror row_mask:0xf bank_mask:0xf bound_ctrl:1
	v_readlane_b32 s3, v160, 16
	v_readlane_b32 s28, v160, 48
	v_readlane_b32 s29, v194, 16
	v_readlane_b32 s30, v194, 48
	v_readlane_b32 s24, v160, 0
	v_readlane_b32 s25, v194, 0
	v_readlane_b32 s26, v160, 32
	v_readlane_b32 s27, v194, 32
	v_mov_b32_e32 v94, s3
	v_mov_b32_e32 v95, s29
	v_mov_b32_e32 v96, s28
	v_mov_b32_e32 v97, s30
	v_pk_add_f32 v[94:95], s[24:25], v[94:95]
	v_pk_add_f32 v[96:97], s[26:27], v[96:97]
	v_readlane_b32 s3, v231, 16
	v_readlane_b32 s28, v231, 48
	v_readlane_b32 s29, v232, 16
	v_readlane_b32 s30, v232, 48
	v_readlane_b32 s24, v231, 0
	v_readlane_b32 s25, v232, 0
	v_readlane_b32 s26, v231, 32
	v_readlane_b32 s27, v232, 32
	v_pk_add_f32 v[94:95], v[94:95], v[96:97]
	v_mov_b32_e32 v98, s3
	v_mov_b32_e32 v99, s29
	v_mov_b32_e32 v100, s28
	v_mov_b32_e32 v101, s30
	v_cndmask_b32_e32 v82, v82, v94, vcc
	v_cndmask_b32_e32 v33, v33, v95, vcc
	v_pk_add_f32 v[98:99], s[24:25], v[98:99]
	v_pk_add_f32 v[100:101], s[26:27], v[100:101]
	s_waitcnt vmcnt(10)
; DEVI void phase_p7(const int TIDX, const int BIDX, const int GDIM, KAP KA, unsigned char* WSB, float* OUTB, int l, unsigned char* smem) {
;     ...
; #pragma unroll 4
;       for (int c = 0; c < 36; ++c) {
;         float4 wv[4];
; #pragma unroll
;         for (int j = 0; j < 4; ++j) wv[j] = *(const float4*)(WR + c * 1024 + j * 256 + lane * 4);
; #pragma unroll
;         for (int t = 0; t < 4; ++t) {
;           float s = 0.f;
; #pragma unroll
;           for (int j = 0; j < 4; ++j) s += v[t][j].x * wv[j].x + v[t][j].y * wv[j].y + v[t][j].z * wv[j].z + v[t][j].w * wv[j].w;
;           s = wave_sum(s);
;           if (lane == c) mine[t] = s;
;         }
;       }
	v_mov_b32_e32 v252, v162
	v_mov_b32_e32 v253, v166
	v_pk_add_f32 v[98:99], v[98:99], v[100:101]
	v_mov_b32_e32 v166, v163
	v_mov_b32_e32 v158, v164
	v_mov_b32_e32 v159, v168
	v_mov_b32_e32 v168, v165
	v_cndmask_b32_e32 v0, v0, v98, vcc
	v_cndmask_b32_e32 v1, v1, v99, vcc
	v_pk_mul_f32 v[244:245], v[26:27], v[166:167]
	v_pk_mul_f32 v[246:247], v[56:57], v[166:167]
	v_pk_mul_f32 v[248:249], v[4:5], v[166:167]
	v_pk_mul_f32 v[250:251], v[20:21], v[166:167]
	v_pk_fma_f32 v[244:245], v[24:25], v[252:253], v[244:245]
	v_pk_fma_f32 v[246:247], v[54:55], v[252:253], v[246:247]
	v_pk_fma_f32 v[248:249], v[16:17], v[252:253], v[248:249]
	v_pk_fma_f32 v[250:251], v[14:15], v[252:253], v[250:251]
	v_pk_fma_f32 v[244:245], v[28:29], v[158:159], v[244:245]
	v_pk_fma_f32 v[246:247], v[58:59], v[158:159], v[246:247]
	v_pk_fma_f32 v[248:249], v[18:19], v[158:159], v[248:249]
	v_pk_fma_f32 v[250:251], v[22:23], v[158:159], v[250:251]
	v_pk_fma_f32 v[244:245], v[30:31], v[168:169], v[244:245]
	v_pk_fma_f32 v[246:247], v[60:61], v[168:169], v[246:247]
	v_pk_fma_f32 v[248:249], v[2:3], v[168:169], v[248:249]
	v_pk_fma_f32 v[250:251], v[70:71], v[168:169], v[250:251]
	v_add_f32_e32 v160, 0, v244
	v_add_f32_e32 v194, 0, v246
	v_add_f32_e32 v231, 0, v248
	v_add_f32_e32 v232, 0, v250
	v_add_f32_e32 v160, v160, v245
	v_add_f32_e32 v194, v194, v247
	v_add_f32_e32 v231, v231, v249
	v_add_f32_e32 v232, v232, v251
	s_waitcnt vmcnt(8)
	v_mov_b32_e32 v252, v170
	v_mov_b32_e32 v253, v174
	v_mov_b32_e32 v174, v171
	v_mov_b32_e32 v158, v172
	v_mov_b32_e32 v159, v176
	v_mov_b32_e32 v176, v173
	v_pk_mul_f32 v[244:245], v[48:49], v[174:175]
	v_pk_mul_f32 v[246:247], v[64:65], v[174:175]
	v_pk_mul_f32 v[248:249], v[8:9], v[174:175]
	v_pk_mul_f32 v[250:251], v[74:75], v[174:175]
	v_pk_fma_f32 v[244:245], v[46:47], v[252:253], v[244:245]
	v_pk_fma_f32 v[246:247], v[62:63], v[252:253], v[246:247]
	v_pk_fma_f32 v[248:249], v[6:7], v[252:253], v[248:249]
	v_pk_fma_f32 v[250:251], v[72:73], v[252:253], v[250:251]
	v_pk_fma_f32 v[244:245], v[50:51], v[158:159], v[244:245]
	v_pk_fma_f32 v[246:247], v[66:67], v[158:159], v[246:247]
	v_pk_fma_f32 v[248:249], v[12:13], v[158:159], v[248:249]
	v_pk_fma_f32 v[250:251], v[76:77], v[158:159], v[250:251]
	v_pk_fma_f32 v[244:245], v[52:53], v[176:177], v[244:245]
	v_pk_fma_f32 v[246:247], v[68:69], v[176:177], v[246:247]
	v_pk_fma_f32 v[248:249], v[10:11], v[176:177], v[248:249]
	v_pk_fma_f32 v[250:251], v[78:79], v[176:177], v[250:251]
	v_add_f32_e32 v160, v160, v244
	v_add_f32_e32 v194, v194, v246
	v_add_f32_e32 v231, v231, v248
	v_add_f32_e32 v232, v232, v250
	v_add_f32_e32 v160, v160, v245
	v_add_f32_e32 v194, v194, v247
	v_add_f32_e32 v231, v231, v249
	v_add_f32_e32 v232, v232, v251
	s_or_b32 s101, s2, 1
	v_cmp_eq_u32_e32 vcc, s101, v45
	v_add_f32_dpp v160, v160, v160 quad_perm:[1,0,3,2] row_mask:0xf bank_mask:0xf bound_ctrl:1
	v_add_f32_dpp v194, v194, v194 quad_perm:[1,0,3,2] row_mask:0xf bank_mask:0xf bound_ctrl:1
	v_add_f32_dpp v231, v231, v231 quad_perm:[1,0,3,2] row_mask:0xf bank_mask:0xf bound_ctrl:1
	v_add_f32_dpp v232, v232, v232 quad_perm:[1,0,3,2] row_mask:0xf bank_mask:0xf bound_ctrl:1
	v_add_f32_dpp v160, v160, v160 quad_perm:[2,3,0,1] row_mask:0xf bank_mask:0xf bound_ctrl:1
	v_add_f32_dpp v194, v194, v194 quad_perm:[2,3,0,1] row_mask:0xf bank_mask:0xf bound_ctrl:1
	v_add_f32_dpp v231, v231, v231 quad_perm:[2,3,0,1] row_mask:0xf bank_mask:0xf bound_ctrl:1
	v_add_f32_dpp v232, v232, v232 quad_perm:[2,3,0,1] row_mask:0xf bank_mask:0xf bound_ctrl:1
	v_add_f32_dpp v160, v160, v160 row_half_mirror row_mask:0xf bank_mask:0xf bound_ctrl:1
	v_add_f32_dpp v194, v194, v194 row_half_mirror row_mask:0xf bank_mask:0xf bound_ctrl:1
	v_add_f32_dpp v231, v231, v231 row_half_mirror row_mask:0xf bank_mask:0xf bound_ctrl:1
	v_add_f32_dpp v232, v232, v232 row_half_mirror row_mask:0xf bank_mask:0xf bound_ctrl:1
	v_add_f32_dpp v160, v160, v160 row_mirror row_mask:0xf bank_mask:0xf bound_ctrl:1
	v_add_f32_dpp v194, v194, v194 row_mirror row_mask:0xf bank_mask:0xf bound_ctrl:1
	v_add_f32_dpp v231, v231, v231 row_mirror row_mask:0xf bank_mask:0xf bound_ctrl:1
	v_add_f32_dpp v232, v232, v232 row_mirror row_mask:0xf bank_mask:0xf bound_ctrl:1
	v_readlane_b32 s3, v160, 16
	v_readlane_b32 s28, v160, 48
	v_readlane_b32 s29, v194, 16
	v_readlane_b32 s30, v194, 48
	v_readlane_b32 s24, v160, 0
	v_readlane_b32 s25, v194, 0
	v_readlane_b32 s26, v160, 32
	v_readlane_b32 s27, v194, 32
	v_mov_b32_e32 v94, s3
	v_mov_b32_e32 v95, s29
	v_mov_b32_e32 v96, s28
	v_mov_b32_e32 v97, s30
	v_pk_add_f32 v[94:95], s[24:25], v[94:95]
	v_pk_add_f32 v[96:97], s[26:27], v[96:97]
	v_readlane_b32 s3, v231, 16
	v_readlane_b32 s28, v231, 48
	v_readlane_b32 s29, v232, 16
	v_readlane_b32 s30, v232, 48
	v_readlane_b32 s24, v231, 0
	v_readlane_b32 s25, v232, 0
	v_readlane_b32 s26, v231, 32
	v_readlane_b32 s27, v232, 32
	v_pk_add_f32 v[94:95], v[94:95], v[96:97]
	v_mov_b32_e32 v98, s3
	v_mov_b32_e32 v99, s29
	v_mov_b32_e32 v100, s28
	v_mov_b32_e32 v101, s30
	v_cndmask_b32_e32 v82, v82, v94, vcc
	v_cndmask_b32_e32 v33, v33, v95, vcc
	v_pk_add_f32 v[98:99], s[24:25], v[98:99]
	v_pk_add_f32 v[100:101], s[26:27], v[100:101]
	s_waitcnt vmcnt(6)
; DEVI void phase_p7(const int TIDX, const int BIDX, const int GDIM, KAP KA, unsigned char* WSB, float* OUTB, int l, unsigned char* smem) {
;     ...
; #pragma unroll 4
;       for (int c = 0; c < 36; ++c) {
;         float4 wv[4];
; #pragma unroll
;         for (int j = 0; j < 4; ++j) wv[j] = *(const float4*)(WR + c * 1024 + j * 256 + lane * 4);
; #pragma unroll
;         for (int t = 0; t < 4; ++t) {
;           float s = 0.f;
; #pragma unroll
;           for (int j = 0; j < 4; ++j) s += v[t][j].x * wv[j].x + v[t][j].y * wv[j].y + v[t][j].z * wv[j].z + v[t][j].w * wv[j].w;
;           s = wave_sum(s);
;           if (lane == c) mine[t] = s;
;         }
;       }
	v_mov_b32_e32 v252, v178
	v_mov_b32_e32 v253, v182
	v_pk_add_f32 v[98:99], v[98:99], v[100:101]
	v_mov_b32_e32 v182, v179
	v_mov_b32_e32 v158, v180
	v_mov_b32_e32 v159, v184
	v_mov_b32_e32 v184, v181
	v_cndmask_b32_e32 v0, v0, v98, vcc
	v_cndmask_b32_e32 v1, v1, v99, vcc
	v_pk_mul_f32 v[244:245], v[26:27], v[182:183]
	v_pk_mul_f32 v[246:247], v[56:57], v[182:183]
	v_pk_mul_f32 v[248:249], v[4:5], v[182:183]
	v_pk_mul_f32 v[250:251], v[20:21], v[182:183]
	v_pk_fma_f32 v[244:245], v[24:25], v[252:253], v[244:245]
	v_pk_fma_f32 v[246:247], v[54:55], v[252:253], v[246:247]
	v_pk_fma_f32 v[248:249], v[16:17], v[252:253], v[248:249]
	v_pk_fma_f32 v[250:251], v[14:15], v[252:253], v[250:251]
	v_pk_fma_f32 v[244:245], v[28:29], v[158:159], v[244:245]
	v_pk_fma_f32 v[246:247], v[58:59], v[158:159], v[246:247]
	v_pk_fma_f32 v[248:249], v[18:19], v[158:159], v[248:249]
	v_pk_fma_f32 v[250:251], v[22:23], v[158:159], v[250:251]
	v_pk_fma_f32 v[244:245], v[30:31], v[184:185], v[244:245]
	v_pk_fma_f32 v[246:247], v[60:61], v[184:185], v[246:247]
	v_pk_fma_f32 v[248:249], v[2:3], v[184:185], v[248:249]
	v_pk_fma_f32 v[250:251], v[70:71], v[184:185], v[250:251]
	v_add_f32_e32 v160, 0, v244
	v_add_f32_e32 v194, 0, v246
	v_add_f32_e32 v231, 0, v248
	v_add_f32_e32 v232, 0, v250
	v_add_f32_e32 v160, v160, v245
	v_add_f32_e32 v194, v194, v247
	v_add_f32_e32 v231, v231, v249
	v_add_f32_e32 v232, v232, v251
	s_waitcnt vmcnt(4)
	v_mov_b32_e32 v252, v186
	v_mov_b32_e32 v253, v190
	v_mov_b32_e32 v190, v187
	v_mov_b32_e32 v158, v188
	v_mov_b32_e32 v159, v192
	v_mov_b32_e32 v192, v189
	v_pk_mul_f32 v[244:245], v[48:49], v[190:191]
	v_pk_mul_f32 v[246:247], v[64:65], v[190:191]
	v_pk_mul_f32 v[248:249], v[8:9], v[190:191]
	v_pk_mul_f32 v[250:251], v[74:75], v[190:191]
	v_pk_fma_f32 v[244:245], v[46:47], v[252:253], v[244:245]
	v_pk_fma_f32 v[246:247], v[62:63], v[252:253], v[246:247]
	v_pk_fma_f32 v[248:249], v[6:7], v[252:253], v[248:249]
	v_pk_fma_f32 v[250:251], v[72:73], v[252:253], v[250:251]
	v_pk_fma_f32 v[244:245], v[50:51], v[158:159], v[244:245]
	v_pk_fma_f32 v[246:247], v[66:67], v[158:159], v[246:247]
	v_pk_fma_f32 v[248:249], v[12:13], v[158:159], v[248:249]
	v_pk_fma_f32 v[250:251], v[76:77], v[158:159], v[250:251]
	v_pk_fma_f32 v[244:245], v[52:53], v[192:193], v[244:245]
	v_pk_fma_f32 v[246:247], v[68:69], v[192:193], v[246:247]
	v_pk_fma_f32 v[248:249], v[10:11], v[192:193], v[248:249]
	v_pk_fma_f32 v[250:251], v[78:79], v[192:193], v[250:251]
	v_add_f32_e32 v160, v160, v244
	v_add_f32_e32 v194, v194, v246
	v_add_f32_e32 v231, v231, v248
	v_add_f32_e32 v232, v232, v250
	v_add_f32_e32 v160, v160, v245
	v_add_f32_e32 v194, v194, v247
	v_add_f32_e32 v231, v231, v249
	v_add_f32_e32 v232, v232, v251
	s_or_b32 s101, s2, 2
	v_cmp_eq_u32_e32 vcc, s101, v45
	v_add_f32_dpp v160, v160, v160 quad_perm:[1,0,3,2] row_mask:0xf bank_mask:0xf bound_ctrl:1
	v_add_f32_dpp v194, v194, v194 quad_perm:[1,0,3,2] row_mask:0xf bank_mask:0xf bound_ctrl:1
	v_add_f32_dpp v231, v231, v231 quad_perm:[1,0,3,2] row_mask:0xf bank_mask:0xf bound_ctrl:1
	v_add_f32_dpp v232, v232, v232 quad_perm:[1,0,3,2] row_mask:0xf bank_mask:0xf bound_ctrl:1
	v_add_f32_dpp v160, v160, v160 quad_perm:[2,3,0,1] row_mask:0xf bank_mask:0xf bound_ctrl:1
	v_add_f32_dpp v194, v194, v194 quad_perm:[2,3,0,1] row_mask:0xf bank_mask:0xf bound_ctrl:1
	v_add_f32_dpp v231, v231, v231 quad_perm:[2,3,0,1] row_mask:0xf bank_mask:0xf bound_ctrl:1
	v_add_f32_dpp v232, v232, v232 quad_perm:[2,3,0,1] row_mask:0xf bank_mask:0xf bound_ctrl:1
	v_add_f32_dpp v160, v160, v160 row_half_mirror row_mask:0xf bank_mask:0xf bound_ctrl:1
	v_add_f32_dpp v194, v194, v194 row_half_mirror row_mask:0xf bank_mask:0xf bound_ctrl:1
	v_add_f32_dpp v231, v231, v231 row_half_mirror row_mask:0xf bank_mask:0xf bound_ctrl:1
	v_add_f32_dpp v232, v232, v232 row_half_mirror row_mask:0xf bank_mask:0xf bound_ctrl:1
	v_add_f32_dpp v160, v160, v160 row_mirror row_mask:0xf bank_mask:0xf bound_ctrl:1
	v_add_f32_dpp v194, v194, v194 row_mirror row_mask:0xf bank_mask:0xf bound_ctrl:1
	v_add_f32_dpp v231, v231, v231 row_mirror row_mask:0xf bank_mask:0xf bound_ctrl:1
	v_add_f32_dpp v232, v232, v232 row_mirror row_mask:0xf bank_mask:0xf bound_ctrl:1
	v_readlane_b32 s3, v160, 16
	v_readlane_b32 s28, v160, 48
	v_readlane_b32 s29, v194, 16
	v_readlane_b32 s30, v194, 48
	v_readlane_b32 s24, v160, 0
	v_readlane_b32 s25, v194, 0
	v_readlane_b32 s26, v160, 32
	v_readlane_b32 s27, v194, 32
	v_mov_b32_e32 v94, s3
	v_mov_b32_e32 v95, s29
	v_mov_b32_e32 v96, s28
	v_mov_b32_e32 v97, s30
	v_pk_add_f32 v[94:95], s[24:25], v[94:95]
	v_pk_add_f32 v[96:97], s[26:27], v[96:97]
	v_readlane_b32 s3, v231, 16
	v_readlane_b32 s28, v231, 48
	v_readlane_b32 s29, v232, 16
	v_readlane_b32 s30, v232, 48
	v_readlane_b32 s24, v231, 0
	v_readlane_b32 s25, v232, 0
	v_readlane_b32 s26, v231, 32
	v_readlane_b32 s27, v232, 32
	v_pk_add_f32 v[94:95], v[94:95], v[96:97]
	v_mov_b32_e32 v98, s3
	v_mov_b32_e32 v99, s29
	v_mov_b32_e32 v100, s28
	v_mov_b32_e32 v101, s30
	v_cndmask_b32_e32 v82, v82, v94, vcc
	v_cndmask_b32_e32 v33, v33, v95, vcc
	v_pk_add_f32 v[98:99], s[24:25], v[98:99]
	v_pk_add_f32 v[100:101], s[26:27], v[100:101]
	s_waitcnt vmcnt(2)
; DEVI void phase_p7(const int TIDX, const int BIDX, const int GDIM, KAP KA, unsigned char* WSB, float* OUTB, int l, unsigned char* smem) {
;     ...
; #pragma unroll 4
;       for (int c = 0; c < 36; ++c) {
;         float4 wv[4];
; #pragma unroll
;         for (int j = 0; j < 4; ++j) wv[j] = *(const float4*)(WR + c * 1024 + j * 256 + lane * 4);
; #pragma unroll
;         for (int t = 0; t < 4; ++t) {
;           float s = 0.f;
; #pragma unroll
;           for (int j = 0; j < 4; ++j) s += v[t][j].x * wv[j].x + v[t][j].y * wv[j].y + v[t][j].z * wv[j].z + v[t][j].w * wv[j].w;
;           s = wave_sum(s);
;           if (lane == c) mine[t] = s;
;         }
;       }
	v_mov_b32_e32 v252, v196
	v_mov_b32_e32 v253, v200
	v_pk_add_f32 v[98:99], v[98:99], v[100:101]
	v_mov_b32_e32 v200, v197
	v_mov_b32_e32 v158, v198
	v_mov_b32_e32 v159, v202
	v_mov_b32_e32 v202, v199
	v_cndmask_b32_e32 v0, v0, v98, vcc
	v_cndmask_b32_e32 v1, v1, v99, vcc
	v_pk_mul_f32 v[244:245], v[26:27], v[200:201]
	v_pk_mul_f32 v[246:247], v[56:57], v[200:201]
	v_pk_mul_f32 v[248:249], v[4:5], v[200:201]
	v_pk_mul_f32 v[250:251], v[20:21], v[200:201]
	v_pk_fma_f32 v[244:245], v[24:25], v[252:253], v[244:245]
	v_pk_fma_f32 v[246:247], v[54:55], v[252:253], v[246:247]
	v_pk_fma_f32 v[248:249], v[16:17], v[252:253], v[248:249]
	v_pk_fma_f32 v[250:251], v[14:15], v[252:253], v[250:251]
	v_pk_fma_f32 v[244:245], v[28:29], v[158:159], v[244:245]
	v_pk_fma_f32 v[246:247], v[58:59], v[158:159], v[246:247]
	v_pk_fma_f32 v[248:249], v[18:19], v[158:159], v[248:249]
	v_pk_fma_f32 v[250:251], v[22:23], v[158:159], v[250:251]
	v_pk_fma_f32 v[244:245], v[30:31], v[202:203], v[244:245]
	v_pk_fma_f32 v[246:247], v[60:61], v[202:203], v[246:247]
	v_pk_fma_f32 v[248:249], v[2:3], v[202:203], v[248:249]
	v_pk_fma_f32 v[250:251], v[70:71], v[202:203], v[250:251]
	v_add_f32_e32 v160, 0, v244
	v_add_f32_e32 v194, 0, v246
	v_add_f32_e32 v231, 0, v248
	v_add_f32_e32 v232, 0, v250
	v_add_f32_e32 v160, v160, v245
	v_add_f32_e32 v194, v194, v247
	v_add_f32_e32 v231, v231, v249
	v_add_f32_e32 v232, v232, v251
	s_waitcnt vmcnt(0)
	v_mov_b32_e32 v252, v236
	v_mov_b32_e32 v253, v240
	v_mov_b32_e32 v240, v237
	v_mov_b32_e32 v158, v238
	v_mov_b32_e32 v159, v242
	v_mov_b32_e32 v242, v239
	v_pk_mul_f32 v[244:245], v[48:49], v[240:241]
	v_pk_mul_f32 v[246:247], v[64:65], v[240:241]
	v_pk_mul_f32 v[248:249], v[8:9], v[240:241]
	v_pk_mul_f32 v[250:251], v[74:75], v[240:241]
	v_pk_fma_f32 v[244:245], v[46:47], v[252:253], v[244:245]
	v_pk_fma_f32 v[246:247], v[62:63], v[252:253], v[246:247]
	v_pk_fma_f32 v[248:249], v[6:7], v[252:253], v[248:249]
	v_pk_fma_f32 v[250:251], v[72:73], v[252:253], v[250:251]
	v_pk_fma_f32 v[244:245], v[50:51], v[158:159], v[244:245]
	v_pk_fma_f32 v[246:247], v[66:67], v[158:159], v[246:247]
	v_pk_fma_f32 v[248:249], v[12:13], v[158:159], v[248:249]
	v_pk_fma_f32 v[250:251], v[76:77], v[158:159], v[250:251]
	v_pk_fma_f32 v[244:245], v[52:53], v[242:243], v[244:245]
	v_pk_fma_f32 v[246:247], v[68:69], v[242:243], v[246:247]
	v_pk_fma_f32 v[248:249], v[10:11], v[242:243], v[248:249]
	v_pk_fma_f32 v[250:251], v[78:79], v[242:243], v[250:251]
	v_add_f32_e32 v160, v160, v244
	v_add_f32_e32 v194, v194, v246
	v_add_f32_e32 v231, v231, v248
	v_add_f32_e32 v232, v232, v250
	v_add_f32_e32 v160, v160, v245
	v_add_f32_e32 v194, v194, v247
	v_add_f32_e32 v231, v231, v249
	v_add_f32_e32 v232, v232, v251
	s_or_b32 s101, s2, 3
	v_cmp_eq_u32_e32 vcc, s101, v45
	v_add_f32_dpp v160, v160, v160 quad_perm:[1,0,3,2] row_mask:0xf bank_mask:0xf bound_ctrl:1
	v_add_f32_dpp v194, v194, v194 quad_perm:[1,0,3,2] row_mask:0xf bank_mask:0xf bound_ctrl:1
	v_add_f32_dpp v231, v231, v231 quad_perm:[1,0,3,2] row_mask:0xf bank_mask:0xf bound_ctrl:1
	v_add_f32_dpp v232, v232, v232 quad_perm:[1,0,3,2] row_mask:0xf bank_mask:0xf bound_ctrl:1
	v_add_f32_dpp v160, v160, v160 quad_perm:[2,3,0,1] row_mask:0xf bank_mask:0xf bound_ctrl:1
	v_add_f32_dpp v194, v194, v194 quad_perm:[2,3,0,1] row_mask:0xf bank_mask:0xf bound_ctrl:1
	v_add_f32_dpp v231, v231, v231 quad_perm:[2,3,0,1] row_mask:0xf bank_mask:0xf bound_ctrl:1
	v_add_f32_dpp v232, v232, v232 quad_perm:[2,3,0,1] row_mask:0xf bank_mask:0xf bound_ctrl:1
	v_add_f32_dpp v160, v160, v160 row_half_mirror row_mask:0xf bank_mask:0xf bound_ctrl:1
	v_add_f32_dpp v194, v194, v194 row_half_mirror row_mask:0xf bank_mask:0xf bound_ctrl:1
	v_add_f32_dpp v231, v231, v231 row_half_mirror row_mask:0xf bank_mask:0xf bound_ctrl:1
	v_add_f32_dpp v232, v232, v232 row_half_mirror row_mask:0xf bank_mask:0xf bound_ctrl:1
	v_add_f32_dpp v160, v160, v160 row_mirror row_mask:0xf bank_mask:0xf bound_ctrl:1
	v_add_f32_dpp v194, v194, v194 row_mirror row_mask:0xf bank_mask:0xf bound_ctrl:1
	v_add_f32_dpp v231, v231, v231 row_mirror row_mask:0xf bank_mask:0xf bound_ctrl:1
	v_add_f32_dpp v232, v232, v232 row_mirror row_mask:0xf bank_mask:0xf bound_ctrl:1
	v_readlane_b32 s3, v160, 16
	v_readlane_b32 s28, v160, 48
	v_readlane_b32 s29, v194, 16
	v_readlane_b32 s30, v194, 48
	v_readlane_b32 s24, v160, 0
	v_readlane_b32 s25, v194, 0
	v_readlane_b32 s26, v160, 32
	v_readlane_b32 s27, v194, 32
	v_mov_b32_e32 v94, s3
	v_mov_b32_e32 v95, s29
	v_mov_b32_e32 v96, s28
	v_mov_b32_e32 v97, s30
	v_pk_add_f32 v[94:95], s[24:25], v[94:95]
	v_pk_add_f32 v[96:97], s[26:27], v[96:97]
	v_readlane_b32 s3, v231, 16
	v_readlane_b32 s28, v231, 48
	v_readlane_b32 s29, v232, 16
	v_readlane_b32 s30, v232, 48
	v_readlane_b32 s24, v231, 0
	v_readlane_b32 s25, v232, 0
	v_readlane_b32 s26, v231, 32
	v_readlane_b32 s27, v232, 32
	v_pk_add_f32 v[94:95], v[94:95], v[96:97]
	v_mov_b32_e32 v98, s3
	v_mov_b32_e32 v99, s29
	v_mov_b32_e32 v100, s28
	v_mov_b32_e32 v101, s30
	v_cndmask_b32_e32 v82, v82, v94, vcc
	v_cndmask_b32_e32 v33, v33, v95, vcc
	v_pk_add_f32 v[98:99], s[24:25], v[98:99]
	v_pk_add_f32 v[100:101], s[26:27], v[100:101]
	s_add_i32 s2, s2, 4
	v_pk_add_f32 v[98:99], v[98:99], v[100:101]
	s_add_u32 s0, s0, 0x4000
	s_addc_u32 s1, s1, 0
	v_cndmask_b32_e32 v0, v0, v98, vcc
	v_cndmask_b32_e32 v1, v1, v99, vcc
	s_cmp_eq_u32 s2, 36
	s_cbranch_scc0 .LBB0_69
; DEVI void phase_p7(const int TIDX, const int BIDX, const int GDIM, KAP KA, unsigned char* WSB, float* OUTB, int l, unsigned char* smem) {
;     ...
;       for (int t = 0; t < 4; ++t) {
;         const int tok = r4 * 4 + t;
;         float gl[4];
; #pragma unroll
;         for (int j = 0; j < 4; ++j) gl[j] = __shfl(mine[t], j);
;         int gi = 0; float gm = gl[0];
; #pragma unroll
;         for (int j = 1; j < 4; ++j) if (gl[j] > gm) { gm = gl[j]; gi = j; }
;         float gs = 0.f;
; #pragma unroll
;         for (int j = 0; j < 4; ++j) gs += expf(gl[j] - gm);
;         const float gtop = 1.f / gs;
;         float el[8];
; #pragma unroll
;         for (int j = 0; j < 8; ++j) el[j] = __shfl(mine[t], 4 + gi * 8 + j);
;         float em = el[0];
; #pragma unroll
;         for (int j = 1; j < 8; ++j) em = fmaxf(em, el[j]);
;         float pe[8], es = 0.f;
; #pragma unroll
;         for (int j = 0; j < 8; ++j) { pe[j] = expf(el[j] - em); es += pe[j]; }
	v_bfe_u32 v154, v45, 1, 2
	ds_bpermute_b32 v2, v85, v82
	ds_bpermute_b32 v3, v86, v82
	ds_bpermute_b32 v4, v87, v82
	ds_bpermute_b32 v5, v88, v82
	ds_bpermute_b32 v142, v85, v33
	ds_bpermute_b32 v143, v86, v33
	ds_bpermute_b32 v144, v87, v33
	ds_bpermute_b32 v145, v88, v33
	ds_bpermute_b32 v146, v85, v0
	ds_bpermute_b32 v147, v86, v0
	ds_bpermute_b32 v148, v87, v0
	ds_bpermute_b32 v149, v88, v0
	ds_bpermute_b32 v150, v85, v1
	ds_bpermute_b32 v151, v86, v1
	ds_bpermute_b32 v152, v87, v1
	ds_bpermute_b32 v153, v88, v1
	s_waitcnt lgkmcnt(0)
	v_cmp_eq_u32_e32 vcc, 1, v154
	s_nop 1
	v_cndmask_b32_e32 v2, v2, v142, vcc
	v_cndmask_b32_e32 v3, v3, v143, vcc
	v_cndmask_b32_e32 v4, v4, v144, vcc
	v_cndmask_b32_e32 v5, v5, v145, vcc
	v_cmp_eq_u32_e32 vcc, 2, v154
	s_nop 1
	v_cndmask_b32_e32 v2, v2, v146, vcc
	v_cndmask_b32_e32 v3, v3, v147, vcc
	v_cndmask_b32_e32 v4, v4, v148, vcc
	v_cndmask_b32_e32 v5, v5, v149, vcc
	v_cmp_eq_u32_e32 vcc, 3, v154
	s_nop 1
	v_cndmask_b32_e32 v2, v2, v150, vcc
	v_cndmask_b32_e32 v3, v3, v151, vcc
	v_cndmask_b32_e32 v4, v4, v152, vcc
	v_cndmask_b32_e32 v5, v5, v153, vcc
	s_waitcnt lgkmcnt(2)
	v_cmp_gt_f32_e32 vcc, v3, v2
	s_nop 1
	v_cndmask_b32_e32 v6, v2, v3, vcc
	s_waitcnt lgkmcnt(1)
	v_cmp_lt_f32_e64 s[22:23], v6, v4
	s_nop 1
	v_cndmask_b32_e64 v6, v6, v4, s[22:23]
	s_waitcnt lgkmcnt(0)
	v_cmp_lt_f32_e64 s[24:25], v6, v5
	s_nop 1
	v_cndmask_b32_e64 v6, v6, v5, s[24:25]
	v_sub_f32_e32 v7, v2, v6
	v_sub_f32_e32 v2, v3, v6
	v_mul_f32_e32 v3, 0x3fb8aa3b, v2
	v_fma_f32 v8, v2, s61, -v3
	v_rndne_f32_e32 v9, v3
	v_fmac_f32_e32 v8, 0x32a5705f, v2
	v_sub_f32_e32 v3, v3, v9
	v_add_f32_e32 v3, v3, v8
	v_exp_f32_e32 v3, v3
	v_cvt_i32_f32_e32 v8, v9
	v_cmp_ngt_f32_e64 s[26:27], s90, v2
	v_mul_f32_e32 v16, 0x3fb8aa3b, v7
	v_fma_f32 v17, v7, s61, -v16
	v_ldexp_f32 v3, v3, v8
	v_cndmask_b32_e64 v3, 0, v3, s[26:27]
	v_cmp_nlt_f32_e64 s[26:27], s91, v2
	v_sub_f32_e32 v2, v4, v6
	v_mul_f32_e32 v4, 0x3fb8aa3b, v2
	v_fma_f32 v8, v2, s61, -v4
	v_rndne_f32_e32 v9, v4
	v_fmac_f32_e32 v8, 0x32a5705f, v2
	v_sub_f32_e32 v4, v4, v9
	v_add_f32_e32 v4, v4, v8
	v_exp_f32_e32 v4, v4
	v_cvt_i32_f32_e32 v8, v9
	v_cndmask_b32_e64 v3, v229, v3, s[26:27]
	v_cmp_ngt_f32_e64 s[26:27], s90, v2
	v_rndne_f32_e32 v18, v16
	v_ldexp_f32 v4, v4, v8
	v_cndmask_b32_e64 v4, 0, v4, s[26:27]
	v_cmp_nlt_f32_e64 s[26:27], s91, v2
	v_sub_f32_e32 v2, v5, v6
	v_mul_f32_e32 v5, 0x3fb8aa3b, v2
	v_fma_f32 v6, v2, s61, -v5
	v_rndne_f32_e32 v8, v5
	v_fmac_f32_e32 v6, 0x32a5705f, v2
	v_sub_f32_e32 v5, v5, v8
	v_add_f32_e32 v5, v5, v6
	v_exp_f32_e32 v5, v5
	v_cvt_i32_f32_e32 v6, v8
	v_cndmask_b32_e64 v4, v229, v4, s[26:27]
	v_cmp_ngt_f32_e64 s[26:27], s90, v2
	v_fmac_f32_e32 v17, 0x32a5705f, v7
	v_ldexp_f32 v5, v5, v6
	v_cndmask_b32_e64 v5, 0, v5, s[26:27]
	v_cmp_nlt_f32_e64 s[26:27], s91, v2
	v_sub_f32_e32 v16, v16, v18
	v_add_f32_e32 v16, v16, v17
	v_cndmask_b32_e64 v6, v229, v5, s[26:27]
	v_cndmask_b32_e64 v5, 0, 8, vcc
	v_cndmask_b32_e64 v5, v5, 16, s[22:23]
	v_exp_f32_e32 v16, v16
	v_cvt_i32_f32_e32 v17, v18
	v_cndmask_b32_e64 v5, v5, 24, s[24:25]
	v_or_b32_e32 v8, v5, v84
	v_lshlrev_b32_e32 v8, 2, v8
	v_mov_b32_e32 v155, v8
	ds_bpermute_b32 v9, v8, v82
	ds_bpermute_b32 v10, v8, v82 offset:4
	v_ldexp_f32 v16, v16, v17
	v_cmp_ngt_f32_e32 vcc, s90, v7
	ds_bpermute_b32 v11, v8, v82 offset:8
	ds_bpermute_b32 v12, v8, v82 offset:12
	v_cndmask_b32_e32 v16, 0, v16, vcc
	v_cmp_nlt_f32_e32 vcc, s91, v7
	ds_bpermute_b32 v13, v8, v82 offset:16
	ds_bpermute_b32 v14, v8, v82 offset:20
	v_cndmask_b32_e32 v7, v229, v16, vcc
	v_add_f32_e32 v3, v7, v3
	ds_bpermute_b32 v15, v8, v82 offset:24
	ds_bpermute_b32 v8, v8, v82 offset:28
	ds_bpermute_b32 v156, v155, v33
	ds_bpermute_b32 v157, v155, v33 offset:4
	ds_bpermute_b32 v158, v155, v33 offset:8
	ds_bpermute_b32 v159, v155, v33 offset:12
	ds_bpermute_b32 v160, v155, v33 offset:16
	ds_bpermute_b32 v162, v155, v33 offset:20
	ds_bpermute_b32 v163, v155, v33 offset:24
	ds_bpermute_b32 v164, v155, v33 offset:28
	ds_bpermute_b32 v165, v155, v0
	ds_bpermute_b32 v166, v155, v0 offset:4
	ds_bpermute_b32 v167, v155, v0 offset:8
	ds_bpermute_b32 v168, v155, v0 offset:12
	ds_bpermute_b32 v169, v155, v0 offset:16
	ds_bpermute_b32 v170, v155, v0 offset:20
	ds_bpermute_b32 v171, v155, v0 offset:24
	ds_bpermute_b32 v172, v155, v0 offset:28
	ds_bpermute_b32 v173, v155, v1
	ds_bpermute_b32 v174, v155, v1 offset:4
	ds_bpermute_b32 v175, v155, v1 offset:8
	ds_bpermute_b32 v176, v155, v1 offset:12
	ds_bpermute_b32 v177, v155, v1 offset:16
	ds_bpermute_b32 v178, v155, v1 offset:20
	ds_bpermute_b32 v179, v155, v1 offset:24
	ds_bpermute_b32 v180, v155, v1 offset:28
	v_add_f32_e32 v3, v4, v3
	v_add_f32_e32 v3, v6, v3
	s_waitcnt lgkmcnt(0)
	v_cmp_eq_u32_e32 vcc, 1, v154
	s_nop 1
	v_cndmask_b32_e32 v9, v9, v156, vcc
	v_cndmask_b32_e32 v10, v10, v157, vcc
	v_cndmask_b32_e32 v11, v11, v158, vcc
	v_cndmask_b32_e32 v12, v12, v159, vcc
	v_cndmask_b32_e32 v13, v13, v160, vcc
	v_cndmask_b32_e32 v14, v14, v162, vcc
	v_cndmask_b32_e32 v15, v15, v163, vcc
	v_cndmask_b32_e32 v8, v8, v164, vcc
	v_cmp_eq_u32_e32 vcc, 2, v154
	s_nop 1
	v_cndmask_b32_e32 v9, v9, v165, vcc
	v_cndmask_b32_e32 v10, v10, v166, vcc
	v_cndmask_b32_e32 v11, v11, v167, vcc
	v_cndmask_b32_e32 v12, v12, v168, vcc
	v_cndmask_b32_e32 v13, v13, v169, vcc
	v_cndmask_b32_e32 v14, v14, v170, vcc
	v_cndmask_b32_e32 v15, v15, v171, vcc
	v_cndmask_b32_e32 v8, v8, v172, vcc
	v_cmp_eq_u32_e32 vcc, 3, v154
	s_nop 1
	v_cndmask_b32_e32 v9, v9, v173, vcc
	v_cndmask_b32_e32 v10, v10, v174, vcc
	v_cndmask_b32_e32 v11, v11, v175, vcc
	v_cndmask_b32_e32 v12, v12, v176, vcc
	v_cndmask_b32_e32 v13, v13, v177, vcc
	v_cndmask_b32_e32 v14, v14, v178, vcc
	v_cndmask_b32_e32 v15, v15, v179, vcc
	v_cndmask_b32_e32 v8, v8, v180, vcc
	s_waitcnt lgkmcnt(6)
; DEVI void phase_p7(const int TIDX, const int BIDX, const int GDIM, KAP KA, unsigned char* WSB, float* OUTB, int l, unsigned char* smem) {
;     ...
;         float em = el[0];
; #pragma unroll
;         for (int j = 1; j < 8; ++j) em = fmaxf(em, el[j]);
;         float pe[8], es = 0.f;
; #pragma unroll
;         for (int j = 0; j < 8; ++j) { pe[j] = expf(el[j] - em); es += pe[j]; }
; #pragma unroll
;         for (int j = 0; j < 8; ++j) pe[j] = pe[j] / es;
	v_max_f32_e32 v4, v10, v10
	v_max_f32_e32 v6, v9, v9
	v_max_f32_e32 v4, v6, v4
	s_waitcnt lgkmcnt(4)
	v_max3_f32 v4, v4, v11, v12
	s_waitcnt lgkmcnt(2)
	v_max3_f32 v4, v4, v13, v14
	s_waitcnt lgkmcnt(0)
	v_max3_f32 v4, v4, v15, v8
	v_sub_f32_e32 v6, v9, v4
	v_mul_f32_e32 v7, 0x3fb8aa3b, v6
	v_fma_f32 v9, v6, s61, -v7
	v_rndne_f32_e32 v16, v7
	v_fmac_f32_e32 v9, 0x32a5705f, v6
	v_sub_f32_e32 v7, v7, v16
	v_add_f32_e32 v7, v7, v9
	v_exp_f32_e32 v7, v7
	v_cvt_i32_f32_e32 v9, v16
	v_cmp_ngt_f32_e32 vcc, s90, v6
	v_mov_b32_e32 v2, 0
	v_ldexp_f32 v7, v7, v9
	v_cndmask_b32_e32 v7, 0, v7, vcc
	v_cmp_nlt_f32_e32 vcc, s91, v6
	s_nop 1
	v_cndmask_b32_e32 v6, v229, v7, vcc
	v_sub_f32_e32 v7, v10, v4
	v_mul_f32_e32 v9, 0x3fb8aa3b, v7
	v_fma_f32 v10, v7, s61, -v9
	v_rndne_f32_e32 v16, v9
	v_fmac_f32_e32 v10, 0x32a5705f, v7
	v_sub_f32_e32 v9, v9, v16
	v_add_f32_e32 v9, v9, v10
	v_exp_f32_e32 v9, v9
	v_cvt_i32_f32_e32 v10, v16
	v_cmp_ngt_f32_e32 vcc, s90, v7
	v_ldexp_f32 v9, v9, v10
	v_sub_f32_e32 v10, v11, v4
	v_mul_f32_e32 v11, 0x3fb8aa3b, v10
	v_fma_f32 v16, v10, s61, -v11
	v_rndne_f32_e32 v17, v11
	v_fmac_f32_e32 v16, 0x32a5705f, v10
	v_sub_f32_e32 v11, v11, v17
	v_add_f32_e32 v11, v11, v16
	v_exp_f32_e32 v11, v11
	v_cvt_i32_f32_e32 v16, v17
	v_cndmask_b32_e32 v9, 0, v9, vcc
	v_cmp_nlt_f32_e32 vcc, s91, v7
	v_ldexp_f32 v11, v11, v16
	s_nop 0
	v_cndmask_b32_e32 v7, v229, v9, vcc
	v_cmp_ngt_f32_e32 vcc, s90, v10
	v_add_f32_e32 v9, v6, v7
	s_nop 0
	v_cndmask_b32_e32 v11, 0, v11, vcc
	v_cmp_nlt_f32_e32 vcc, s91, v10
	s_nop 1
	v_cndmask_b32_e32 v10, v229, v11, vcc
	v_sub_f32_e32 v11, v12, v4
	v_mul_f32_e32 v12, 0x3fb8aa3b, v11
	v_fma_f32 v16, v11, s61, -v12
	v_rndne_f32_e32 v17, v12
	v_fmac_f32_e32 v16, 0x32a5705f, v11
	v_sub_f32_e32 v12, v12, v17
	v_add_f32_e32 v12, v12, v16
	v_exp_f32_e32 v12, v12
	v_cvt_i32_f32_e32 v16, v17
	v_cmp_ngt_f32_e32 vcc, s90, v11
	v_add_f32_e32 v9, v10, v9
	v_ldexp_f32 v12, v12, v16
	v_cndmask_b32_e32 v12, 0, v12, vcc
	v_cmp_nlt_f32_e32 vcc, s91, v11
	s_nop 1
	v_cndmask_b32_e32 v11, v229, v12, vcc
	v_sub_f32_e32 v12, v13, v4
	v_mul_f32_e32 v13, 0x3fb8aa3b, v12
	v_fma_f32 v16, v12, s61, -v13
	v_rndne_f32_e32 v17, v13
	v_fmac_f32_e32 v16, 0x32a5705f, v12
	v_sub_f32_e32 v13, v13, v17
	v_add_f32_e32 v13, v13, v16
	v_exp_f32_e32 v13, v13
	v_cvt_i32_f32_e32 v16, v17
	v_cmp_ngt_f32_e32 vcc, s90, v12
	v_add_f32_e32 v9, v11, v9
	v_ldexp_f32 v13, v13, v16
	v_cndmask_b32_e32 v13, 0, v13, vcc
	v_cmp_nlt_f32_e32 vcc, s91, v12
	s_nop 1
	v_cndmask_b32_e32 v12, v229, v13, vcc
	v_sub_f32_e32 v13, v14, v4
	v_mul_f32_e32 v14, 0x3fb8aa3b, v13
	v_fma_f32 v16, v13, s61, -v14
	v_rndne_f32_e32 v17, v14
	v_fmac_f32_e32 v16, 0x32a5705f, v13
	v_sub_f32_e32 v14, v14, v17
	v_add_f32_e32 v14, v14, v16
	v_exp_f32_e32 v14, v14
	v_cvt_i32_f32_e32 v16, v17
	v_cmp_ngt_f32_e32 vcc, s90, v13
	v_add_f32_e32 v9, v12, v9
	v_ldexp_f32 v14, v14, v16
	v_cndmask_b32_e32 v14, 0, v14, vcc
	v_cmp_nlt_f32_e32 vcc, s91, v13
	s_nop 1
	v_cndmask_b32_e32 v13, v229, v14, vcc
	v_sub_f32_e32 v14, v15, v4
	v_mul_f32_e32 v15, 0x3fb8aa3b, v14
	v_fma_f32 v16, v14, s61, -v15
	v_rndne_f32_e32 v17, v15
	v_fmac_f32_e32 v16, 0x32a5705f, v14
	v_sub_f32_e32 v15, v15, v17
	v_add_f32_e32 v15, v15, v16
	v_exp_f32_e32 v15, v15
	v_cvt_i32_f32_e32 v16, v17
	v_cmp_ngt_f32_e32 vcc, s90, v14
	v_sub_f32_e32 v4, v8, v4
	v_mul_f32_e32 v8, 0x3fb8aa3b, v4
	v_ldexp_f32 v15, v15, v16
	v_cndmask_b32_e32 v15, 0, v15, vcc
	v_cmp_nlt_f32_e32 vcc, s91, v14
	v_rndne_f32_e32 v16, v8
	v_add_f32_e32 v9, v13, v9
	v_cndmask_b32_e32 v14, v229, v15, vcc
	v_fma_f32 v15, v4, s61, -v8
	v_fmac_f32_e32 v15, 0x32a5705f, v4
	v_sub_f32_e32 v8, v8, v16
	v_add_f32_e32 v8, v8, v15
	v_exp_f32_e32 v8, v8
	v_cvt_i32_f32_e32 v15, v16
	v_cmp_ngt_f32_e32 vcc, s90, v4
	v_add_f32_e32 v9, v14, v9
	v_ldexp_f32 v8, v8, v15
	v_cndmask_b32_e32 v8, 0, v8, vcc
	v_cmp_nlt_f32_e32 vcc, s91, v4
	s_nop 1
	v_cndmask_b32_e32 v4, v229, v8, vcc
	v_add_f32_e32 v8, v4, v9
	v_div_scale_f32 v9, s[0:1], v8, v8, v6
	v_rcp_f32_e32 v15, v9
	s_nop 0
	v_fma_f32 v16, -v9, v15, 1.0
	v_fmac_f32_e32 v15, v16, v15
	v_div_scale_f32 v16, vcc, v6, v8, v6
	v_mul_f32_e32 v17, v16, v15
	v_fma_f32 v18, -v9, v17, v16
	v_fmac_f32_e32 v17, v18, v15
	v_fma_f32 v9, -v9, v17, v16
	v_div_fmas_f32 v9, v9, v15, v17
	v_div_fixup_f32 v6, v9, v8, v6
	v_div_scale_f32 v9, s[0:1], v8, v8, v7
	v_rcp_f32_e32 v15, v9
	v_cmp_nlt_f32_e64 s[24:25], -1.0, v6
	v_fma_f32 v16, -v9, v15, 1.0
	v_fmac_f32_e32 v15, v16, v15
	v_div_scale_f32 v16, vcc, v7, v8, v7
	v_mul_f32_e32 v17, v16, v15
	v_fma_f32 v18, -v9, v17, v16
	v_fmac_f32_e32 v17, v18, v15
	v_fma_f32 v9, -v9, v17, v16
	v_div_fmas_f32 v9, v9, v15, v17
	v_div_fixup_f32 v9, v9, v8, v7
	v_div_scale_f32 v7, s[0:1], v8, v8, v10
	v_rcp_f32_e32 v15, v7
	s_nop 0
	v_fma_f32 v16, -v7, v15, 1.0
	v_fmac_f32_e32 v15, v16, v15
	v_div_scale_f32 v16, vcc, v10, v8, v10
	v_mul_f32_e32 v17, v16, v15
	v_fma_f32 v18, -v7, v17, v16
	v_fmac_f32_e32 v17, v18, v15
	v_fma_f32 v7, -v7, v17, v16
	v_div_fmas_f32 v7, v7, v15, v17
	v_div_fixup_f32 v10, v7, v8, v10
	v_div_scale_f32 v7, s[0:1], v8, v8, v11
	v_rcp_f32_e32 v15, v7
	s_nop 0
	v_fma_f32 v16, -v7, v15, 1.0
	v_fmac_f32_e32 v15, v16, v15
	v_div_scale_f32 v16, vcc, v11, v8, v11
	v_mul_f32_e32 v17, v16, v15
	v_fma_f32 v18, -v7, v17, v16
	v_fmac_f32_e32 v17, v18, v15
	v_fma_f32 v7, -v7, v17, v16
	v_div_fmas_f32 v7, v7, v15, v17
	v_div_fixup_f32 v11, v7, v8, v11
	v_div_scale_f32 v7, s[0:1], v8, v8, v12
	v_rcp_f32_e32 v15, v7
	s_nop 0
	v_fma_f32 v16, -v7, v15, 1.0
	v_fmac_f32_e32 v15, v16, v15
	v_div_scale_f32 v16, vcc, v12, v8, v12
	v_mul_f32_e32 v17, v16, v15
	v_fma_f32 v18, -v7, v17, v16
; DEVI void phase_p7(const int TIDX, const int BIDX, const int GDIM, KAP KA, unsigned char* WSB, float* OUTB, int l, unsigned char* smem) {
;     ...
;         for (int j = 0; j < 8; ++j) pe[j] = pe[j] / es;
;         int i1 = 0; float p1 = pe[0];
; #pragma unroll
;         for (int j = 1; j < 8; ++j) if (pe[j] > p1) { p1 = pe[j]; i1 = j; }
;         int i2 = -1; float p2 = -1.f;
; #pragma unroll
;         for (int j = 0; j < 8; ++j) if (j != i1 && pe[j] > p2) { p2 = pe[j]; i2 = j; }
;         const float den = p1 + p2;
;         if (lane == 2 * t) { my_e = gi * 8 + i1; my_w = gtop * (p1 / den); my_tk = tok * 2; }
;         if (lane == 2 * t + 1) { my_e = gi * 8 + i2; my_w = gtop * (p2 / den); my_tk = tok * 2 + 1; }
;       }
;       if (lane < 8) {
;         const int sl = atomicAdd(cnt + my_e * 32, 1);
;         ltok[(size_t)my_e * NTOK + sl] = my_tk;
;         lw[(size_t)my_e * NTOK + sl] = my_w;
;       }
	v_fmac_f32_e32 v17, v18, v15
	v_fma_f32 v7, -v7, v17, v16
	v_div_fmas_f32 v7, v7, v15, v17
	v_div_fixup_f32 v12, v7, v8, v12
	v_div_scale_f32 v7, s[0:1], v8, v8, v13
	v_rcp_f32_e32 v15, v7
	s_nop 0
	v_fma_f32 v16, -v7, v15, 1.0
	v_fmac_f32_e32 v15, v16, v15
	v_div_scale_f32 v16, vcc, v13, v8, v13
	v_mul_f32_e32 v17, v16, v15
	v_fma_f32 v18, -v7, v17, v16
	v_fmac_f32_e32 v17, v18, v15
	v_fma_f32 v7, -v7, v17, v16
	v_div_fmas_f32 v7, v7, v15, v17
	v_div_fixup_f32 v13, v7, v8, v13
	v_div_scale_f32 v7, s[0:1], v8, v8, v14
	v_rcp_f32_e32 v15, v7
	s_nop 0
	v_fma_f32 v16, -v7, v15, 1.0
	v_fmac_f32_e32 v15, v16, v15
	v_div_scale_f32 v16, vcc, v14, v8, v14
	v_mul_f32_e32 v17, v16, v15
	v_fma_f32 v18, -v7, v17, v16
	v_fmac_f32_e32 v17, v18, v15
	v_fma_f32 v7, -v7, v17, v16
	v_div_fmas_f32 v7, v7, v15, v17
	v_div_fixup_f32 v14, v7, v8, v14
	v_div_scale_f32 v7, s[0:1], v8, v8, v4
	v_rcp_f32_e32 v15, v7
	s_nop 0
	v_fma_f32 v16, -v7, v15, 1.0
	v_fmac_f32_e32 v15, v16, v15
	v_div_scale_f32 v16, vcc, v4, v8, v4
	v_mul_f32_e32 v17, v16, v15
	v_fma_f32 v18, -v7, v17, v16
	v_fmac_f32_e32 v17, v18, v15
	v_fma_f32 v7, -v7, v17, v16
	v_div_fmas_f32 v7, v7, v15, v17
	v_cmp_gt_f32_e32 vcc, v9, v6
	v_div_fixup_f32 v4, v7, v8, v4
	s_nop 0
	v_cndmask_b32_e32 v8, v6, v9, vcc
	v_cndmask_b32_e64 v7, 0, 1, vcc
	v_cmp_gt_f32_e32 vcc, v10, v8
	s_nop 1
	v_cndmask_b32_e32 v8, v8, v10, vcc
	v_cndmask_b32_e64 v7, v7, 2, vcc
	v_cmp_gt_f32_e32 vcc, v11, v8
	s_nop 1
	v_cndmask_b32_e32 v8, v8, v11, vcc
	v_cndmask_b32_e64 v7, v7, 3, vcc
	v_cmp_gt_f32_e32 vcc, v12, v8
	s_nop 1
	v_cndmask_b32_e32 v8, v8, v12, vcc
	v_cndmask_b32_e64 v7, v7, 4, vcc
	v_cmp_gt_f32_e32 vcc, v13, v8
	s_nop 1
	v_cndmask_b32_e32 v8, v8, v13, vcc
	v_cndmask_b32_e64 v7, v7, 5, vcc
	v_cmp_gt_f32_e32 vcc, v14, v8
	s_nop 1
	v_cndmask_b32_e32 v15, v8, v14, vcc
	v_cndmask_b32_e64 v7, v7, 6, vcc
	v_cmp_ngt_f32_e64 s[36:37], v4, v15
	s_and_b64 s[2:3], vcc, s[36:37]
	s_nop 0
	v_cndmask_b32_e64 v8, 7, v7, s[36:37]
	v_cmp_eq_u32_e64 s[22:23], 0, v8
	s_or_b64 s[0:1], s[24:25], s[22:23]
	v_cndmask_b32_e64 v6, v6, -1.0, s[0:1]
	v_cmp_ne_u32_e64 s[22:23], 1, v8
	v_cmp_gt_f32_e64 s[24:25], v9, v6
	s_and_b64 s[22:23], s[22:23], s[24:25]
	v_cndmask_b32_e64 v6, v6, v9, s[22:23]
	v_cmp_ne_u32_e64 s[24:25], 2, v8
	v_cmp_gt_f32_e64 s[26:27], v10, v6
	s_and_b64 s[24:25], s[24:25], s[26:27]
	v_cndmask_b32_e64 v6, v6, v10, s[24:25]
	v_cmp_ne_u32_e64 s[26:27], 3, v8
	v_cmp_gt_f32_e64 s[28:29], v11, v6
	s_and_b64 s[26:27], s[26:27], s[28:29]
	v_cndmask_b32_e64 v6, v6, v11, s[26:27]
	v_cmp_ne_u32_e64 s[28:29], 4, v8
	v_cmp_gt_f32_e64 s[30:31], v12, v6
	s_and_b64 s[28:29], s[28:29], s[30:31]
	v_cndmask_b32_e64 v6, v6, v12, s[28:29]
	v_cmp_ne_u32_e64 s[30:31], 5, v8
	v_cmp_gt_f32_e64 s[34:35], v13, v6
	s_and_b64 s[34:35], s[30:31], s[34:35]
	v_cndmask_b32_e64 v7, v4, v15, s[36:37]
	v_cndmask_b32_e64 v6, v6, v13, s[34:35]
	v_cmp_ngt_f32_e32 vcc, v14, v6
	s_or_b64 s[30:31], s[2:3], vcc
	v_cndmask_b32_e64 v6, v14, v6, s[30:31]
	v_cmp_gt_f32_e32 vcc, v4, v6
	s_and_b64 s[36:37], s[36:37], vcc
	v_cndmask_b32_e64 v6, v6, v4, s[36:37]
	v_div_scale_f32 v4, s[2:3], v3, v3, 1.0
	v_rcp_f32_e32 v9, v4
	s_nop 0
	v_fma_f32 v10, -v4, v9, 1.0
	v_fmac_f32_e32 v9, v10, v9
	v_div_scale_f32 v10, vcc, 1.0, v3, 1.0
	v_mul_f32_e32 v11, v10, v9
	v_fma_f32 v12, -v4, v11, v10
	v_fmac_f32_e32 v11, v12, v9
	v_fma_f32 v4, -v4, v11, v10
	v_div_fmas_f32 v4, v4, v9, v11
	v_div_fixup_f32 v9, v4, v3, 1.0
	v_add_f32_e32 v10, v7, v6
	v_mov_b32_e32 v4, 0
	v_mov_b32_e32 v3, 0
	s_or_b64 s[62:63], s[6:7], s[10:11]
	s_or_b64 s[62:63], s[62:63], s[14:15]
	s_or_b64 s[62:63], s[62:63], s[18:19]
	s_and_saveexec_b64 s[2:3], s[62:63]
	s_cbranch_execz .LBB0_72
	v_div_scale_f32 v2, s[62:63], v10, v10, v7
	v_rcp_f32_e32 v4, v2
	v_add_u32_e32 v3, v8, v5
	v_fma_f32 v8, -v2, v4, 1.0
	v_fmac_f32_e32 v4, v8, v4
	v_div_scale_f32 v8, vcc, v7, v10, v7
	v_mul_f32_e32 v11, v8, v4
	v_fma_f32 v12, -v2, v11, v8
	v_fmac_f32_e32 v11, v12, v4
	v_fma_f32 v2, -v2, v11, v8
	v_div_fmas_f32 v2, v2, v4, v11
	v_div_fixup_f32 v2, v2, v10, v7
	v_mul_f32_e32 v4, v9, v2
	v_lshl_or_b32 v2, v32, 3, v45
.LBB0_72:
	s_or_b64 exec, exec, s[2:3]
	s_or_b64 s[62:63], s[8:9], s[12:13]
	s_or_b64 s[62:63], s[62:63], s[16:17]
	s_or_b64 s[62:63], s[62:63], s[20:21]
	s_and_saveexec_b64 s[2:3], s[62:63]
	s_cbranch_execz .LBB0_74
	v_cndmask_b32_e64 v2, 0, -1, s[0:1]
	v_cndmask_b32_e64 v2, v2, 1, s[22:23]
	v_cndmask_b32_e64 v2, v2, 2, s[24:25]
	v_cndmask_b32_e64 v2, v2, 3, s[26:27]
	v_div_scale_f32 v4, s[0:1], v10, v10, v6
	v_cndmask_b32_e64 v2, v2, 4, s[28:29]
	v_rcp_f32_e32 v7, v4
	v_cndmask_b32_e64 v2, v2, 5, s[34:35]
	v_cndmask_b32_e64 v2, 6, v2, s[30:31]
	v_cndmask_b32_e64 v2, v2, 7, s[36:37]
	v_add_u32_e32 v3, v2, v5
	v_fma_f32 v2, -v4, v7, 1.0
	v_fmac_f32_e32 v7, v2, v7
	v_div_scale_f32 v2, vcc, v6, v10, v6
	v_mul_f32_e32 v5, v2, v7
	v_fma_f32 v8, -v4, v5, v2
	v_fmac_f32_e32 v5, v8, v7
	v_fma_f32 v2, -v4, v5, v2
	v_div_fmas_f32 v2, v2, v7, v5
	v_div_fixup_f32 v2, v2, v10, v6
	v_mul_f32_e32 v4, v9, v2
	v_lshl_or_b32 v2, v32, 3, v45
.LBB0_74:
	s_or_b64 exec, exec, s[2:3]
	s_and_saveexec_b64 s[0:1], s[4:5]
	s_cbranch_execz .LBB0_67
.LBB0_87:
	v_lshlrev_b32_e32 v0, 5, v3
	v_ashrrev_i32_e32 v1, 31, v0
	v_lshl_add_u64 v[0:1], v[0:1], 2, s[44:45]
	v_mov_b32_e32 v5, 1
	global_atomic_add v0, v[0:1], v5, off sc0
	s_waitcnt vmcnt(0)
	v_ashrrev_i32_e32 v1, 31, v0
	v_mad_i64_i32 v[0:1], s[2:3], v3, s77, v[0:1]
	v_lshlrev_b64 v[0:1], 2, v[0:1]
	v_lshl_add_u64 v[6:7], s[46:47], 0, v[0:1]
	v_lshl_add_u64 v[0:1], s[40:41], 0, v[0:1]
	global_store_dword v[6:7], v2, off
	global_store_dword v[0:1], v4, off
	s_branch .LBB0_67
